# k32: k31 + GEMM K-loop heads issue their first 8 ds_reads before the next-tile pointer/select SALU block
# speedup vs baseline: 1.0050x; 1.0002x over previous
; #define PG8_STAGE(bufoff, gbase, voff) do { _Pragma("unroll") for (int _i = 0; _i < 2; ++_i) \
;         __builtin_amdgcn_global_load_lds((const unsigned*)((const char*)(gbase) + (voff)[_i]), (LAS unsigned*)(lds + (bufoff) + ldsw + _i * 8192), 16, 0, 0); } while (0)
; #define PG8_LDA(dst, b, h) do { _Pragma("unroll") for (int m = 0; m < 4; ++m) _Pragma("unroll") for (int k = 0; k < 2; ++k) dst[m][k] = *(const LAS bf16x8*)(lds + PG8_SA(b, h) + aoff + m * 2048 + k * 1024); } while (0)
; #define PG8_LDB(dst, b, h) do { _Pragma("unroll") for (int n = 0; n < 2; ++n) _Pragma("unroll") for (int k = 0; k < 2; ++k) dst[n][k] = *(const LAS bf16x8*)(lds + PG8_SB(b, h) + boff + n * 2048 + k * 1024); } while (0)
; #define PG8_MMA(ai, bj, At, Bt) do { __builtin_amdgcn_s_setprio(1); _Pragma("unroll") for (int m = 0; m < 4; ++m) _Pragma("unroll") for (int n = 0; n < 2; ++n) _Pragma("unroll") for (int k = 0; k < 2; ++k) \
;         acc[ai][bj][m][n] = __builtin_amdgcn_mfma_f32_16x16x32_bf16(Bt[n][k], At[m][k], acc[ai][bj][m][n], 0, 0, 0); __builtin_amdgcn_s_setprio(0); } while (0)
; #define PG8_WAIT_V(n) asm volatile("s_waitcnt vmcnt(" #n ")" ::: "memory")
; #define PG8_WAIT_L(n) asm volatile("s_waitcnt lgkmcnt(" #n ")" ::: "memory")
; #define PG8_BAR __builtin_amdgcn_s_barrier()
; #define PG8_SCHED __builtin_amdgcn_sched_barrier(0)
; template <class Epi, int K, int lda, class Sched = StaticOrder, bool ALIGN_EPI = true>
; __device__ __forceinline__ void gemm_phase(LAS unsigned char* lds, const Gemm g, const Sched& S, const Epi& E) {
;     ...
;             PG8_LDB(B0, 0, 0); PG8_LDB(B1, 0, 1); PG8_SCHED; PG8_LDA(At, 0, 0); PG8_STAGE(PG8_SA(1, 1), a1 + hstepA, voffA);
;             PG8_WAIT_V(8); PG8_WAIT_L(0); PG8_BAR; PG8_MMA(0, 0, At, B0); PG8_MMA(0, 1, At, B1); PG8_BAR; PG8_SCHED;
;             PG8_LDA(At, 0, 1); PG8_STAGE(PG8_SB(0, 0), b2, voffB); PG8_STAGE(PG8_SB(0, 1), b2 + hstepB, voffB); PG8_STAGE(PG8_SA(0, 0), a2, voffA);
;             PG8_WAIT_V(8); PG8_WAIT_L(0); PG8_BAR; PG8_MMA(1, 0, At, B0); PG8_MMA(1, 1, At, B1); PG8_BAR; PG8_SCHED;
.LBB0_72:
	s_add_i32 s28, 0, 0x10000
	s_add_i32 s29, 0, 0x14000
	v_add_u32_e32 v144, s28, v149
	ds_read_b128 v[154:157], v144
	ds_read_b128 v[158:161], v144 offset:1024
	ds_read_b128 v[162:165], v144 offset:2048
	ds_read_b128 v[166:169], v144 offset:3072
	v_add_u32_e32 v144, s29, v149
	ds_read_b128 v[170:173], v144
	ds_read_b128 v[178:181], v144 offset:1024
	ds_read_b128 v[182:185], v144 offset:2048
	ds_read_b128 v[186:189], v144 offset:3072
	s_add_u32 s26, s74, 0xfff80080
	s_addc_u32 s27, s75, -1
	s_cmp_eq_u32 s25, 28
	s_cselect_b32 s79, s47, s27
	s_cselect_b32 s78, s53, s26
	s_cselect_b32 s77, s45, s24
	s_cselect_b32 s76, vcc_lo, vcc_hi
	v_lshl_add_u64 v[146:147], s[74:75], 0, v[140:141]
	s_add_i32 m0, s80, 0xc000
	ds_read_b128 v[190:193], v151
	ds_read_b128 v[200:203], v151 offset:1024
	ds_read_b128 v[204:207], v151 offset:2048
	ds_read_b128 v[208:211], v151 offset:3072
	ds_read_b128 v[212:215], v151 offset:4096
	ds_read_b128 v[216:219], v151 offset:5120
	ds_read_b128 v[220:223], v151 offset:6144
	ds_read_b128 v[224:227], v151 offset:7168
	global_load_lds_dwordx4 v[146:147], off
	v_lshl_add_u64 v[146:147], s[74:75], 0, v[142:143]
	s_add_i32 m0, s80, 0xe000
	s_nop 0
	global_load_lds_dwordx4 v[146:147], off
	s_waitcnt vmcnt(8)
	s_waitcnt lgkmcnt(0)
	s_barrier
	s_setprio 1
	s_waitcnt lgkmcnt(0)
	v_mfma_f32_16x16x32_bf16 v[124:127], v[154:157], v[190:193], v[124:127]
	v_mfma_f32_16x16x32_bf16 v[120:123], v[162:165], v[190:193], v[120:123]
	v_mfma_f32_16x16x32_bf16 v[108:111], v[154:157], v[204:207], v[108:111]
	v_mfma_f32_16x16x32_bf16 v[104:107], v[162:165], v[204:207], v[104:107]
	v_mfma_f32_16x16x32_bf16 v[92:95], v[154:157], v[212:215], v[92:95]
	v_mfma_f32_16x16x32_bf16 v[88:91], v[162:165], v[212:215], v[88:91]
	v_mfma_f32_16x16x32_bf16 v[76:79], v[154:157], v[220:223], v[76:79]
	v_mfma_f32_16x16x32_bf16 v[72:75], v[162:165], v[220:223], v[72:75]
	v_mfma_f32_16x16x32_bf16 v[124:127], v[158:161], v[200:203], v[124:127]
	v_mfma_f32_16x16x32_bf16 v[120:123], v[166:169], v[200:203], v[120:123]
	v_mfma_f32_16x16x32_bf16 v[108:111], v[158:161], v[208:211], v[108:111]
	v_mfma_f32_16x16x32_bf16 v[104:107], v[166:169], v[208:211], v[104:107]
	v_mfma_f32_16x16x32_bf16 v[92:95], v[158:161], v[216:219], v[92:95]
	v_mfma_f32_16x16x32_bf16 v[88:91], v[166:169], v[216:219], v[88:91]
	v_mfma_f32_16x16x32_bf16 v[76:79], v[158:161], v[224:227], v[76:79]
	v_mfma_f32_16x16x32_bf16 v[72:75], v[166:169], v[224:227], v[72:75]
	s_setprio 0
	s_setprio 1
	v_mfma_f32_16x16x32_bf16 v[116:119], v[170:173], v[190:193], v[116:119]
	v_mfma_f32_16x16x32_bf16 v[112:115], v[182:185], v[190:193], v[112:115]
	v_mfma_f32_16x16x32_bf16 v[100:103], v[170:173], v[204:207], v[100:103]
	v_mfma_f32_16x16x32_bf16 v[96:99], v[182:185], v[204:207], v[96:99]
	v_mfma_f32_16x16x32_bf16 v[84:87], v[170:173], v[212:215], v[84:87]
	v_mfma_f32_16x16x32_bf16 v[80:83], v[182:185], v[212:215], v[80:83]
	v_mfma_f32_16x16x32_bf16 v[68:71], v[170:173], v[220:223], v[68:71]
	v_mfma_f32_16x16x32_bf16 v[64:67], v[182:185], v[220:223], v[64:67]
	v_mfma_f32_16x16x32_bf16 v[116:119], v[178:181], v[200:203], v[116:119]
	v_mfma_f32_16x16x32_bf16 v[112:115], v[186:189], v[200:203], v[112:115]
	v_mfma_f32_16x16x32_bf16 v[100:103], v[178:181], v[208:211], v[100:103]
	v_mfma_f32_16x16x32_bf16 v[96:99], v[186:189], v[208:211], v[96:99]
	v_mfma_f32_16x16x32_bf16 v[84:87], v[178:181], v[216:219], v[84:87]
	v_mfma_f32_16x16x32_bf16 v[80:83], v[186:189], v[216:219], v[80:83]
	v_mfma_f32_16x16x32_bf16 v[68:71], v[178:181], v[224:227], v[68:71]
	v_mfma_f32_16x16x32_bf16 v[64:67], v[186:189], v[224:227], v[64:67]
	s_setprio 0
	s_barrier
	s_add_i32 s26, s28, s16
	v_lshl_add_u64 v[146:147], s[76:77], 0, v[132:133]
	s_mov_b32 m0, s26
	ds_read_b128 v[190:193], v151 offset:16384
	ds_read_b128 v[200:203], v151 offset:17408
	ds_read_b128 v[204:207], v151 offset:18432
	ds_read_b128 v[208:211], v151 offset:19456
	ds_read_b128 v[212:215], v151 offset:20480
	ds_read_b128 v[216:219], v151 offset:21504
	ds_read_b128 v[220:223], v151 offset:22528
	ds_read_b128 v[224:227], v151 offset:23552
	global_load_lds_dwordx4 v[146:147], off
	s_add_i32 m0, s26, 0x2000
	s_add_u32 s26, s76, 0x80000
	v_lshl_add_u64 v[174:175], s[76:77], 0, v[128:129]
	s_addc_u32 s27, s77, 0
	s_add_i32 s28, s29, s16
	global_load_lds_dwordx4 v[174:175], off
	v_lshl_add_u64 v[228:229], s[26:27], 0, v[132:133]
	s_mov_b32 m0, s28
	v_lshl_add_u64 v[230:231], s[78:79], 0, v[130:131]
	global_load_lds_dwordx4 v[228:229], off
	v_lshl_add_u64 v[228:229], s[26:27], 0, v[128:129]
	s_add_i32 m0, s28, 0x2000
	s_nop 0
	global_load_lds_dwordx4 v[228:229], off
	v_lshl_add_u64 v[228:229], s[78:79], 0, v[134:135]
	s_mov_b32 m0, s80
	s_nop 0
	global_load_lds_dwordx4 v[228:229], off
	s_mov_b32 m0, s81
	s_nop 0
	global_load_lds_dwordx4 v[230:231], off
	s_waitcnt vmcnt(8)
	s_waitcnt lgkmcnt(0)
	s_barrier
; #define PG8_STAGE(bufoff, gbase, voff) do { _Pragma("unroll") for (int _i = 0; _i < 2; ++_i) \
;         __builtin_amdgcn_global_load_lds((const unsigned*)((const char*)(gbase) + (voff)[_i]), (LAS unsigned*)(lds + (bufoff) + ldsw + _i * 8192), 16, 0, 0); } while (0)
; #define PG8_LDA(dst, b, h) do { _Pragma("unroll") for (int m = 0; m < 4; ++m) _Pragma("unroll") for (int k = 0; k < 2; ++k) dst[m][k] = *(const LAS bf16x8*)(lds + PG8_SA(b, h) + aoff + m * 2048 + k * 1024); } while (0)
; #define PG8_LDB(dst, b, h) do { _Pragma("unroll") for (int n = 0; n < 2; ++n) _Pragma("unroll") for (int k = 0; k < 2; ++k) dst[n][k] = *(const LAS bf16x8*)(lds + PG8_SB(b, h) + boff + n * 2048 + k * 1024); } while (0)
; #define PG8_MMA(ai, bj, At, Bt) do { __builtin_amdgcn_s_setprio(1); _Pragma("unroll") for (int m = 0; m < 4; ++m) _Pragma("unroll") for (int n = 0; n < 2; ++n) _Pragma("unroll") for (int k = 0; k < 2; ++k) \
;         acc[ai][bj][m][n] = __builtin_amdgcn_mfma_f32_16x16x32_bf16(Bt[n][k], At[m][k], acc[ai][bj][m][n], 0, 0, 0); __builtin_amdgcn_s_setprio(0); } while (0)
; #define PG8_WAIT_V(n) asm volatile("s_waitcnt vmcnt(" #n ")" ::: "memory")
; #define PG8_WAIT_L(n) asm volatile("s_waitcnt lgkmcnt(" #n ")" ::: "memory")
; #define PG8_BAR __builtin_amdgcn_s_barrier()
; #define PG8_SCHED __builtin_amdgcn_sched_barrier(0)
; template <class Epi, int K, int lda, class Sched = StaticOrder, bool ALIGN_EPI = true>
; __device__ __forceinline__ void gemm_phase(LAS unsigned char* lds, const Gemm g, const Sched& S, const Epi& E) {
;     ...
;             PG8_WAIT_V(8); PG8_WAIT_L(0); PG8_BAR; PG8_MMA(1, 0, At, B0); PG8_MMA(1, 1, At, B1); PG8_BAR; PG8_SCHED;
;             PG8_LDB(B0, 1, 0); PG8_LDB(B1, 1, 1); PG8_SCHED; PG8_LDA(At, 1, 0); PG8_STAGE(PG8_SA(0, 1), a2 + hstepA, voffA);
;             PG8_WAIT_V(8); PG8_WAIT_L(0); PG8_BAR; PG8_MMA(0, 0, At, B0); PG8_MMA(0, 1, At, B1); PG8_BAR; PG8_SCHED;
	s_setprio 1
	s_waitcnt lgkmcnt(0)
	v_mfma_f32_16x16x32_bf16 v[60:63], v[154:157], v[190:193], v[60:63]
	v_mfma_f32_16x16x32_bf16 v[56:59], v[162:165], v[190:193], v[56:59]
	v_mfma_f32_16x16x32_bf16 v[44:47], v[154:157], v[204:207], v[44:47]
	v_mfma_f32_16x16x32_bf16 v[40:43], v[162:165], v[204:207], v[40:43]
	v_mfma_f32_16x16x32_bf16 v[28:31], v[154:157], v[212:215], v[28:31]
	v_mfma_f32_16x16x32_bf16 v[24:27], v[162:165], v[212:215], v[24:27]
	v_mfma_f32_16x16x32_bf16 v[12:15], v[154:157], v[220:223], v[12:15]
	v_mfma_f32_16x16x32_bf16 v[8:11], v[162:165], v[220:223], v[8:11]
	v_mfma_f32_16x16x32_bf16 v[60:63], v[158:161], v[200:203], v[60:63]
	v_mfma_f32_16x16x32_bf16 v[56:59], v[166:169], v[200:203], v[56:59]
	v_mfma_f32_16x16x32_bf16 v[44:47], v[158:161], v[208:211], v[44:47]
	v_mfma_f32_16x16x32_bf16 v[40:43], v[166:169], v[208:211], v[40:43]
	v_mfma_f32_16x16x32_bf16 v[28:31], v[158:161], v[216:219], v[28:31]
	v_mfma_f32_16x16x32_bf16 v[24:27], v[166:169], v[216:219], v[24:27]
	v_mfma_f32_16x16x32_bf16 v[12:15], v[158:161], v[224:227], v[12:15]
	v_mfma_f32_16x16x32_bf16 v[8:11], v[166:169], v[224:227], v[8:11]
	s_setprio 0
	s_setprio 1
	v_mfma_f32_16x16x32_bf16 v[52:55], v[170:173], v[190:193], v[52:55]
	v_mfma_f32_16x16x32_bf16 v[48:51], v[182:185], v[190:193], v[48:51]
	v_mfma_f32_16x16x32_bf16 v[36:39], v[170:173], v[204:207], v[36:39]
	v_mfma_f32_16x16x32_bf16 v[32:35], v[182:185], v[204:207], v[32:35]
	v_mfma_f32_16x16x32_bf16 v[20:23], v[170:173], v[212:215], v[20:23]
	v_mfma_f32_16x16x32_bf16 v[16:19], v[182:185], v[212:215], v[16:19]
	v_mfma_f32_16x16x32_bf16 v[4:7], v[170:173], v[220:223], v[4:7]
	v_mfma_f32_16x16x32_bf16 v[0:3], v[182:185], v[220:223], v[0:3]
	v_mfma_f32_16x16x32_bf16 v[52:55], v[178:181], v[200:203], v[52:55]
	v_mfma_f32_16x16x32_bf16 v[48:51], v[186:189], v[200:203], v[48:51]
	v_mfma_f32_16x16x32_bf16 v[36:39], v[178:181], v[208:211], v[36:39]
	v_mfma_f32_16x16x32_bf16 v[32:35], v[186:189], v[208:211], v[32:35]
	v_mfma_f32_16x16x32_bf16 v[20:23], v[178:181], v[216:219], v[20:23]
	v_mfma_f32_16x16x32_bf16 v[16:19], v[186:189], v[216:219], v[16:19]
	v_mfma_f32_16x16x32_bf16 v[4:7], v[178:181], v[224:227], v[4:7]
	v_mfma_f32_16x16x32_bf16 v[0:3], v[186:189], v[224:227], v[0:3]
	s_setprio 0
	s_barrier
	s_add_i32 s28, 0, 0x18000
	v_add_u32_e32 v144, s28, v149
	s_add_i32 s29, 0, 0x1c000
	ds_read_b128 v[154:157], v144
	ds_read_b128 v[158:161], v144 offset:1024
	ds_read_b128 v[162:165], v144 offset:2048
	ds_read_b128 v[166:169], v144 offset:3072
	v_add_u32_e32 v144, s29, v149
	ds_read_b128 v[170:173], v144
	ds_read_b128 v[178:181], v144 offset:1024
	ds_read_b128 v[182:185], v144 offset:2048
	ds_read_b128 v[186:189], v144 offset:3072
	s_add_u32 s26, s78, 0x80000
	s_addc_u32 s27, s79, 0
	s_mov_b32 m0, s82
	v_lshl_add_u64 v[232:233], s[26:27], 0, v[134:135]
	ds_read_b128 v[190:193], v151 offset:32768
	ds_read_b128 v[200:203], v151 offset:33792
	ds_read_b128 v[204:207], v151 offset:34816
	ds_read_b128 v[208:211], v151 offset:35840
	ds_read_b128 v[212:215], v151 offset:36864
	ds_read_b128 v[216:219], v151 offset:37888
	ds_read_b128 v[220:223], v151 offset:38912
	ds_read_b128 v[224:227], v151 offset:39936
	global_load_lds_dwordx4 v[232:233], off
	v_lshl_add_u64 v[232:233], s[26:27], 0, v[130:131]
	s_mov_b32 m0, s83
	s_nop 0
	global_load_lds_dwordx4 v[232:233], off
	s_waitcnt vmcnt(8)
	s_waitcnt lgkmcnt(0)
	s_barrier
	s_setprio 1
	s_waitcnt lgkmcnt(0)
	v_mfma_f32_16x16x32_bf16 v[124:127], v[154:157], v[190:193], v[124:127]
	v_mfma_f32_16x16x32_bf16 v[120:123], v[162:165], v[190:193], v[120:123]
	v_mfma_f32_16x16x32_bf16 v[108:111], v[154:157], v[204:207], v[108:111]
	v_mfma_f32_16x16x32_bf16 v[104:107], v[162:165], v[204:207], v[104:107]
	v_mfma_f32_16x16x32_bf16 v[92:95], v[154:157], v[212:215], v[92:95]
	v_mfma_f32_16x16x32_bf16 v[88:91], v[162:165], v[212:215], v[88:91]
	v_mfma_f32_16x16x32_bf16 v[76:79], v[154:157], v[220:223], v[76:79]
	v_mfma_f32_16x16x32_bf16 v[72:75], v[162:165], v[220:223], v[72:75]
	v_mfma_f32_16x16x32_bf16 v[124:127], v[158:161], v[200:203], v[124:127]
	v_mfma_f32_16x16x32_bf16 v[120:123], v[166:169], v[200:203], v[120:123]
	v_mfma_f32_16x16x32_bf16 v[108:111], v[158:161], v[208:211], v[108:111]
	v_mfma_f32_16x16x32_bf16 v[104:107], v[166:169], v[208:211], v[104:107]
	v_mfma_f32_16x16x32_bf16 v[92:95], v[158:161], v[216:219], v[92:95]
	v_mfma_f32_16x16x32_bf16 v[88:91], v[166:169], v[216:219], v[88:91]
	v_mfma_f32_16x16x32_bf16 v[76:79], v[158:161], v[224:227], v[76:79]
	v_mfma_f32_16x16x32_bf16 v[72:75], v[166:169], v[224:227], v[72:75]
	s_setprio 0
	s_setprio 1
	v_mfma_f32_16x16x32_bf16 v[116:119], v[170:173], v[190:193], v[116:119]
	v_mfma_f32_16x16x32_bf16 v[112:115], v[182:185], v[190:193], v[112:115]
	v_mfma_f32_16x16x32_bf16 v[100:103], v[170:173], v[204:207], v[100:103]
	v_mfma_f32_16x16x32_bf16 v[96:99], v[182:185], v[204:207], v[96:99]
	v_mfma_f32_16x16x32_bf16 v[84:87], v[170:173], v[212:215], v[84:87]
	v_mfma_f32_16x16x32_bf16 v[80:83], v[182:185], v[212:215], v[80:83]
	v_mfma_f32_16x16x32_bf16 v[68:71], v[170:173], v[220:223], v[68:71]
	v_mfma_f32_16x16x32_bf16 v[64:67], v[182:185], v[220:223], v[64:67]
	v_mfma_f32_16x16x32_bf16 v[116:119], v[178:181], v[200:203], v[116:119]
	v_mfma_f32_16x16x32_bf16 v[112:115], v[186:189], v[200:203], v[112:115]
	v_mfma_f32_16x16x32_bf16 v[100:103], v[178:181], v[208:211], v[100:103]
	v_mfma_f32_16x16x32_bf16 v[96:99], v[186:189], v[208:211], v[96:99]
	v_mfma_f32_16x16x32_bf16 v[84:87], v[178:181], v[216:219], v[84:87]
	v_mfma_f32_16x16x32_bf16 v[80:83], v[186:189], v[216:219], v[80:83]
	v_mfma_f32_16x16x32_bf16 v[68:71], v[178:181], v[224:227], v[68:71]
	v_mfma_f32_16x16x32_bf16 v[64:67], v[186:189], v[224:227], v[64:67]
	s_setprio 0
	s_barrier
; #define PG8_STAGE(bufoff, gbase, voff) do { _Pragma("unroll") for (int _i = 0; _i < 2; ++_i) \
;         __builtin_amdgcn_global_load_lds((const unsigned*)((const char*)(gbase) + (voff)[_i]), (LAS unsigned*)(lds + (bufoff) + ldsw + _i * 8192), 16, 0, 0); } while (0)
; #define PG8_LDA(dst, b, h) do { _Pragma("unroll") for (int m = 0; m < 4; ++m) _Pragma("unroll") for (int k = 0; k < 2; ++k) dst[m][k] = *(const LAS bf16x8*)(lds + PG8_SA(b, h) + aoff + m * 2048 + k * 1024); } while (0)
; #define PG8_MMA(ai, bj, At, Bt) do { __builtin_amdgcn_s_setprio(1); _Pragma("unroll") for (int m = 0; m < 4; ++m) _Pragma("unroll") for (int n = 0; n < 2; ++n) _Pragma("unroll") for (int k = 0; k < 2; ++k) \
;         acc[ai][bj][m][n] = __builtin_amdgcn_mfma_f32_16x16x32_bf16(Bt[n][k], At[m][k], acc[ai][bj][m][n], 0, 0, 0); __builtin_amdgcn_s_setprio(0); } while (0)
; #define PG8_WAIT_V(n) asm volatile("s_waitcnt vmcnt(" #n ")" ::: "memory")
; #define PG8_WAIT_L(n) asm volatile("s_waitcnt lgkmcnt(" #n ")" ::: "memory")
; #define PG8_BAR __builtin_amdgcn_s_barrier()
; #define PG8_SCHED __builtin_amdgcn_sched_barrier(0)
; template <class Epi, int K, int lda, class Sched = StaticOrder, bool ALIGN_EPI = true>
; __device__ __forceinline__ void gemm_phase(LAS unsigned char* lds, const Gemm g, const Sched& S, const Epi& E) {
;     ...
;             PG8_LDA(At, 1, 1); PG8_STAGE(PG8_SB(1, 0), b3, voffB); PG8_STAGE(PG8_SB(1, 1), b3 + hstepB, voffB); PG8_STAGE(PG8_SA(1, 0), a3, voffA);
;             PG8_WAIT_V(8); PG8_WAIT_L(0); PG8_BAR; PG8_MMA(1, 0, At, B0); PG8_MMA(1, 1, At, B1); PG8_BAR; PG8_SCHED;
;         }
;         if constexpr (ALIGN_EPI) { if (wr == 0) PG8_BAR; }
	s_add_i32 s26, s28, s16
	v_lshl_add_u64 v[146:147], v[146:147], 0, s[66:67]
	s_mov_b32 m0, s26
	ds_read_b128 v[190:193], v151 offset:49152
	ds_read_b128 v[200:203], v151 offset:50176
	ds_read_b128 v[204:207], v151 offset:51200
	ds_read_b128 v[208:211], v151 offset:52224
	ds_read_b128 v[212:215], v151 offset:53248
	ds_read_b128 v[216:219], v151 offset:54272
	ds_read_b128 v[220:223], v151 offset:55296
	ds_read_b128 v[224:227], v151 offset:56320
	global_load_lds_dwordx4 v[146:147], off
	s_add_i32 m0, s26, 0x2000
	s_add_u32 s26, s76, 0x80080
	v_lshl_add_u64 v[146:147], v[174:175], 0, s[66:67]
	s_addc_u32 s27, s77, 0
	s_add_i32 s28, s29, s16
	global_load_lds_dwordx4 v[146:147], off
	v_lshl_add_u64 v[146:147], s[26:27], 0, v[132:133]
	s_mov_b32 m0, s28
	s_nop 0
	global_load_lds_dwordx4 v[146:147], off
	v_lshl_add_u64 v[146:147], s[26:27], 0, v[128:129]
	s_add_i32 m0, s28, 0x2000
	s_nop 0
	global_load_lds_dwordx4 v[146:147], off
	v_lshl_add_u64 v[146:147], v[228:229], 0, s[66:67]
	s_mov_b32 m0, s86
	s_nop 0
	global_load_lds_dwordx4 v[146:147], off
	v_lshl_add_u64 v[146:147], v[230:231], 0, s[66:67]
	s_mov_b32 m0, s87
	s_nop 0
	global_load_lds_dwordx4 v[146:147], off
	s_waitcnt vmcnt(8)
	s_waitcnt lgkmcnt(0)
	s_barrier
	s_setprio 1
	s_waitcnt lgkmcnt(0)
	v_mfma_f32_16x16x32_bf16 v[60:63], v[154:157], v[190:193], v[60:63]
	v_mfma_f32_16x16x32_bf16 v[56:59], v[162:165], v[190:193], v[56:59]
	v_mfma_f32_16x16x32_bf16 v[44:47], v[154:157], v[204:207], v[44:47]
	v_mfma_f32_16x16x32_bf16 v[40:43], v[162:165], v[204:207], v[40:43]
	v_mfma_f32_16x16x32_bf16 v[28:31], v[154:157], v[212:215], v[28:31]
	v_mfma_f32_16x16x32_bf16 v[24:27], v[162:165], v[212:215], v[24:27]
	v_mfma_f32_16x16x32_bf16 v[12:15], v[154:157], v[220:223], v[12:15]
	v_mfma_f32_16x16x32_bf16 v[8:11], v[162:165], v[220:223], v[8:11]
	v_mfma_f32_16x16x32_bf16 v[60:63], v[158:161], v[200:203], v[60:63]
	v_mfma_f32_16x16x32_bf16 v[56:59], v[166:169], v[200:203], v[56:59]
	v_mfma_f32_16x16x32_bf16 v[44:47], v[158:161], v[208:211], v[44:47]
	v_mfma_f32_16x16x32_bf16 v[40:43], v[166:169], v[208:211], v[40:43]
	v_mfma_f32_16x16x32_bf16 v[28:31], v[158:161], v[216:219], v[28:31]
	v_mfma_f32_16x16x32_bf16 v[24:27], v[166:169], v[216:219], v[24:27]
	v_mfma_f32_16x16x32_bf16 v[12:15], v[158:161], v[224:227], v[12:15]
	v_mfma_f32_16x16x32_bf16 v[8:11], v[166:169], v[224:227], v[8:11]
	s_setprio 0
	s_setprio 1
	v_mfma_f32_16x16x32_bf16 v[52:55], v[170:173], v[190:193], v[52:55]
	v_mfma_f32_16x16x32_bf16 v[48:51], v[182:185], v[190:193], v[48:51]
	v_mfma_f32_16x16x32_bf16 v[36:39], v[170:173], v[204:207], v[36:39]
	v_mfma_f32_16x16x32_bf16 v[32:35], v[182:185], v[204:207], v[32:35]
	v_mfma_f32_16x16x32_bf16 v[20:23], v[170:173], v[212:215], v[20:23]
	v_mfma_f32_16x16x32_bf16 v[16:19], v[182:185], v[212:215], v[16:19]
	v_mfma_f32_16x16x32_bf16 v[4:7], v[170:173], v[220:223], v[4:7]
	v_mfma_f32_16x16x32_bf16 v[0:3], v[182:185], v[220:223], v[0:3]
	v_mfma_f32_16x16x32_bf16 v[52:55], v[178:181], v[200:203], v[52:55]
	v_mfma_f32_16x16x32_bf16 v[48:51], v[186:189], v[200:203], v[48:51]
	v_mfma_f32_16x16x32_bf16 v[36:39], v[178:181], v[208:211], v[36:39]
	v_mfma_f32_16x16x32_bf16 v[32:35], v[186:189], v[208:211], v[32:35]
	v_mfma_f32_16x16x32_bf16 v[20:23], v[178:181], v[216:219], v[20:23]
	v_mfma_f32_16x16x32_bf16 v[16:19], v[186:189], v[216:219], v[16:19]
	v_mfma_f32_16x16x32_bf16 v[4:7], v[178:181], v[224:227], v[4:7]
	v_mfma_f32_16x16x32_bf16 v[0:3], v[186:189], v[224:227], v[0:3]
	s_setprio 0
	s_add_i32 s25, s25, 2
	s_add_u32 s74, s74, 0x100
	s_addc_u32 s75, s75, 0
	s_add_u32 vcc_hi, vcc_hi, 0x100
	s_addc_u32 s24, s24, 0
	s_cmp_gt_u32 s25, 29
	s_barrier
	s_cbranch_scc0 .LBB0_72
	s_and_b64 vcc, exec, s[42:43]
	s_cbranch_vccz .LBB0_75
	s_barrier

; #define PG8_STAGE(bufoff, gbase, voff) do { _Pragma("unroll") for (int _i = 0; _i < 2; ++_i) \
;         __builtin_amdgcn_global_load_lds((const unsigned*)((const char*)(gbase) + (voff)[_i]), (LAS unsigned*)(lds + (bufoff) + ldsw + _i * 8192), 16, 0, 0); } while (0)
; #define PG8_LDA(dst, b, h) do { _Pragma("unroll") for (int m = 0; m < 4; ++m) _Pragma("unroll") for (int k = 0; k < 2; ++k) dst[m][k] = *(const LAS bf16x8*)(lds + PG8_SA(b, h) + aoff + m * 2048 + k * 1024); } while (0)
; #define PG8_LDB(dst, b, h) do { _Pragma("unroll") for (int n = 0; n < 2; ++n) _Pragma("unroll") for (int k = 0; k < 2; ++k) dst[n][k] = *(const LAS bf16x8*)(lds + PG8_SB(b, h) + boff + n * 2048 + k * 1024); } while (0)
; #define PG8_MMA(ai, bj, At, Bt) do { __builtin_amdgcn_s_setprio(1); _Pragma("unroll") for (int m = 0; m < 4; ++m) _Pragma("unroll") for (int n = 0; n < 2; ++n) _Pragma("unroll") for (int k = 0; k < 2; ++k) \
;         acc[ai][bj][m][n] = __builtin_amdgcn_mfma_f32_16x16x32_bf16(Bt[n][k], At[m][k], acc[ai][bj][m][n], 0, 0, 0); __builtin_amdgcn_s_setprio(0); } while (0)
; #define PG8_WAIT_V(n) asm volatile("s_waitcnt vmcnt(" #n ")" ::: "memory")
; #define PG8_WAIT_L(n) asm volatile("s_waitcnt lgkmcnt(" #n ")" ::: "memory")
; #define PG8_BAR __builtin_amdgcn_s_barrier()
; #define PG8_SCHED __builtin_amdgcn_sched_barrier(0)
; template <class Epi, int K, int lda, class Sched = StaticOrder, bool ALIGN_EPI = true>
; __device__ __forceinline__ void gemm_phase(LAS unsigned char* lds, const Gemm g, const Sched& S, const Epi& E) {
;     ...
;             const bool last = (t == nt - 2);
;             const char* a1 = cA + (size_t)(t + 1) * kstep;
;             const char* a2 = last ? nA : cA + (size_t)(t + 2) * kstep; const char* b2 = last ? nB : cB + (size_t)(t + 2) * kstep;
;             const char* a3 = a2 + kstep; const char* b3 = b2 + kstep;
;             PG8_LDB(B0, 0, 0); PG8_LDB(B1, 0, 1); PG8_SCHED; PG8_LDA(At, 0, 0); PG8_STAGE(PG8_SA(1, 1), a1 + hstepA, voffA);
;             PG8_WAIT_V(8); PG8_WAIT_L(0); PG8_BAR; PG8_MMA(0, 0, At, B0); PG8_MMA(0, 1, At, B1); PG8_BAR; PG8_SCHED;
;             PG8_LDA(At, 0, 1); PG8_STAGE(PG8_SB(0, 0), b2, voffB); PG8_STAGE(PG8_SB(0, 1), b2 + hstepB, voffB); PG8_STAGE(PG8_SA(0, 0), a2, voffA);
;             PG8_WAIT_V(8); PG8_WAIT_L(0); PG8_BAR; PG8_MMA(1, 0, At, B0); PG8_MMA(1, 1, At, B1); PG8_BAR; PG8_SCHED;
.LBB0_366:
	s_add_i32 s23, 0, 0x10000
	s_add_i32 s26, 0, 0x14000
	v_add_u32_e32 v150, s23, v161
	ds_read_b128 v[146:149], v150
	ds_read_b128 v[172:175], v150 offset:1024
	ds_read_b128 v[178:181], v150 offset:2048
	ds_read_b128 v[182:185], v150 offset:3072
	v_add_u32_e32 v150, s26, v161
	ds_read_b128 v[186:189], v150
	ds_read_b128 v[190:193], v150 offset:1024
	ds_read_b128 v[200:203], v150 offset:2048
	ds_read_b128 v[204:207], v150 offset:3072
	s_add_u32 s80, s40, 0x100
	s_addc_u32 s81, s41, 0
	s_cmp_eq_u32 s22, 60
	s_cselect_b32 s85, s77, s81
	s_cselect_b32 s84, s76, s80
	s_cselect_b32 s83, s49, s79
	s_cselect_b32 s82, s48, s78
	v_lshl_add_u64 v[150:151], s[40:41], 0, v[142:143]
	s_add_i32 m0, s14, 0xc000
	ds_read_b128 v[208:211], v170
	ds_read_b128 v[212:215], v170 offset:1024
	ds_read_b128 v[216:219], v170 offset:2048
	ds_read_b128 v[220:223], v170 offset:3072
	ds_read_b128 v[224:227], v170 offset:4096
	ds_read_b128 v[228:231], v170 offset:5120
	ds_read_b128 v[232:235], v170 offset:6144
	ds_read_b128 v[236:239], v170 offset:7168
	global_load_lds_dwordx4 v[150:151], off
	v_lshl_add_u64 v[150:151], s[40:41], 0, v[144:145]
	s_add_i32 m0, s14, 0xe000
	s_nop 0
	global_load_lds_dwordx4 v[150:151], off
	s_waitcnt vmcnt(8)
	s_waitcnt lgkmcnt(0)
	s_barrier
	s_setprio 1
	s_waitcnt lgkmcnt(0)
	v_mfma_f32_16x16x32_bf16 v[124:127], v[146:149], v[208:211], v[124:127]
	v_mfma_f32_16x16x32_bf16 v[120:123], v[178:181], v[208:211], v[120:123]
	v_mfma_f32_16x16x32_bf16 v[108:111], v[146:149], v[216:219], v[108:111]
	v_mfma_f32_16x16x32_bf16 v[104:107], v[178:181], v[216:219], v[104:107]
	v_mfma_f32_16x16x32_bf16 v[92:95], v[146:149], v[224:227], v[92:95]
	v_mfma_f32_16x16x32_bf16 v[88:91], v[178:181], v[224:227], v[88:91]
	v_mfma_f32_16x16x32_bf16 v[76:79], v[146:149], v[232:235], v[76:79]
	v_mfma_f32_16x16x32_bf16 v[72:75], v[178:181], v[232:235], v[72:75]
	v_mfma_f32_16x16x32_bf16 v[124:127], v[172:175], v[212:215], v[124:127]
	v_mfma_f32_16x16x32_bf16 v[120:123], v[182:185], v[212:215], v[120:123]
	v_mfma_f32_16x16x32_bf16 v[108:111], v[172:175], v[220:223], v[108:111]
	v_mfma_f32_16x16x32_bf16 v[104:107], v[182:185], v[220:223], v[104:107]
	v_mfma_f32_16x16x32_bf16 v[92:95], v[172:175], v[228:231], v[92:95]
	v_mfma_f32_16x16x32_bf16 v[88:91], v[182:185], v[228:231], v[88:91]
	v_mfma_f32_16x16x32_bf16 v[76:79], v[172:175], v[236:239], v[76:79]
	v_mfma_f32_16x16x32_bf16 v[72:75], v[182:185], v[236:239], v[72:75]
	s_setprio 0
	s_setprio 1
	v_mfma_f32_16x16x32_bf16 v[116:119], v[186:189], v[208:211], v[116:119]
	v_mfma_f32_16x16x32_bf16 v[112:115], v[200:203], v[208:211], v[112:115]
	v_mfma_f32_16x16x32_bf16 v[100:103], v[186:189], v[216:219], v[100:103]
	v_mfma_f32_16x16x32_bf16 v[96:99], v[200:203], v[216:219], v[96:99]
	v_mfma_f32_16x16x32_bf16 v[84:87], v[186:189], v[224:227], v[84:87]
	v_mfma_f32_16x16x32_bf16 v[80:83], v[200:203], v[224:227], v[80:83]
	v_mfma_f32_16x16x32_bf16 v[68:71], v[186:189], v[232:235], v[68:71]
	v_mfma_f32_16x16x32_bf16 v[64:67], v[200:203], v[232:235], v[64:67]
	v_mfma_f32_16x16x32_bf16 v[116:119], v[190:193], v[212:215], v[116:119]
	v_mfma_f32_16x16x32_bf16 v[112:115], v[204:207], v[212:215], v[112:115]
	v_mfma_f32_16x16x32_bf16 v[100:103], v[190:193], v[220:223], v[100:103]
	v_mfma_f32_16x16x32_bf16 v[96:99], v[204:207], v[220:223], v[96:99]
	v_mfma_f32_16x16x32_bf16 v[84:87], v[190:193], v[228:231], v[84:87]
	v_mfma_f32_16x16x32_bf16 v[80:83], v[204:207], v[228:231], v[80:83]
	v_mfma_f32_16x16x32_bf16 v[68:71], v[190:193], v[236:239], v[68:71]
	v_mfma_f32_16x16x32_bf16 v[64:67], v[204:207], v[236:239], v[64:67]
	s_setprio 0
	s_barrier
	s_add_i32 s23, s23, s87
	v_lshl_add_u64 v[150:151], s[82:83], 0, v[130:131]
	s_mov_b32 m0, s23
	ds_read_b128 v[208:211], v170 offset:16384
	ds_read_b128 v[212:215], v170 offset:17408
	ds_read_b128 v[216:219], v170 offset:18432
	ds_read_b128 v[220:223], v170 offset:19456
	ds_read_b128 v[224:227], v170 offset:20480
	ds_read_b128 v[228:231], v170 offset:21504
	ds_read_b128 v[232:235], v170 offset:22528
	ds_read_b128 v[236:239], v170 offset:23552
	global_load_lds_dwordx4 v[150:151], off
	s_add_i32 m0, s23, 0x2000
	s_add_u32 s24, s82, 0x100000
	v_lshl_add_u64 v[194:195], s[82:83], 0, v[134:135]
	s_addc_u32 s25, s83, 0
	s_add_i32 s23, s26, s87
	global_load_lds_dwordx4 v[194:195], off
	v_lshl_add_u64 v[196:197], s[24:25], 0, v[130:131]
	s_mov_b32 m0, s23
	v_lshl_add_u64 v[240:241], s[84:85], 0, v[132:133]
	global_load_lds_dwordx4 v[196:197], off
	v_lshl_add_u64 v[196:197], s[24:25], 0, v[134:135]
	s_add_i32 m0, s23, 0x2000
	s_nop 0
	global_load_lds_dwordx4 v[196:197], off
	v_lshl_add_u64 v[196:197], s[84:85], 0, v[128:129]
	s_mov_b32 m0, s14
	s_nop 0
	global_load_lds_dwordx4 v[196:197], off
	s_mov_b32 m0, s15
	s_nop 0
	global_load_lds_dwordx4 v[240:241], off
	s_waitcnt vmcnt(8)
	s_waitcnt lgkmcnt(0)
	s_barrier
; #define PG8_STAGE(bufoff, gbase, voff) do { _Pragma("unroll") for (int _i = 0; _i < 2; ++_i) \
;         __builtin_amdgcn_global_load_lds((const unsigned*)((const char*)(gbase) + (voff)[_i]), (LAS unsigned*)(lds + (bufoff) + ldsw + _i * 8192), 16, 0, 0); } while (0)
; #define PG8_LDA(dst, b, h) do { _Pragma("unroll") for (int m = 0; m < 4; ++m) _Pragma("unroll") for (int k = 0; k < 2; ++k) dst[m][k] = *(const LAS bf16x8*)(lds + PG8_SA(b, h) + aoff + m * 2048 + k * 1024); } while (0)
; #define PG8_LDB(dst, b, h) do { _Pragma("unroll") for (int n = 0; n < 2; ++n) _Pragma("unroll") for (int k = 0; k < 2; ++k) dst[n][k] = *(const LAS bf16x8*)(lds + PG8_SB(b, h) + boff + n * 2048 + k * 1024); } while (0)
; #define PG8_MMA(ai, bj, At, Bt) do { __builtin_amdgcn_s_setprio(1); _Pragma("unroll") for (int m = 0; m < 4; ++m) _Pragma("unroll") for (int n = 0; n < 2; ++n) _Pragma("unroll") for (int k = 0; k < 2; ++k) \
;         acc[ai][bj][m][n] = __builtin_amdgcn_mfma_f32_16x16x32_bf16(Bt[n][k], At[m][k], acc[ai][bj][m][n], 0, 0, 0); __builtin_amdgcn_s_setprio(0); } while (0)
; #define PG8_WAIT_V(n) asm volatile("s_waitcnt vmcnt(" #n ")" ::: "memory")
; #define PG8_WAIT_L(n) asm volatile("s_waitcnt lgkmcnt(" #n ")" ::: "memory")
; #define PG8_BAR __builtin_amdgcn_s_barrier()
; #define PG8_SCHED __builtin_amdgcn_sched_barrier(0)
; template <class Epi, int K, int lda, class Sched = StaticOrder, bool ALIGN_EPI = true>
; __device__ __forceinline__ void gemm_phase(LAS unsigned char* lds, const Gemm g, const Sched& S, const Epi& E) {
;     ...
;             PG8_WAIT_V(8); PG8_WAIT_L(0); PG8_BAR; PG8_MMA(1, 0, At, B0); PG8_MMA(1, 1, At, B1); PG8_BAR; PG8_SCHED;
;             PG8_LDB(B0, 1, 0); PG8_LDB(B1, 1, 1); PG8_SCHED; PG8_LDA(At, 1, 0); PG8_STAGE(PG8_SA(0, 1), a2 + hstepA, voffA);
;             PG8_WAIT_V(8); PG8_WAIT_L(0); PG8_BAR; PG8_MMA(0, 0, At, B0); PG8_MMA(0, 1, At, B1); PG8_BAR; PG8_SCHED;
	s_setprio 1
	s_waitcnt lgkmcnt(0)
	v_mfma_f32_16x16x32_bf16 v[60:63], v[146:149], v[208:211], v[60:63]
	v_mfma_f32_16x16x32_bf16 v[56:59], v[178:181], v[208:211], v[56:59]
	v_mfma_f32_16x16x32_bf16 v[44:47], v[146:149], v[216:219], v[44:47]
	v_mfma_f32_16x16x32_bf16 v[40:43], v[178:181], v[216:219], v[40:43]
	v_mfma_f32_16x16x32_bf16 v[28:31], v[146:149], v[224:227], v[28:31]
	v_mfma_f32_16x16x32_bf16 v[24:27], v[178:181], v[224:227], v[24:27]
	v_mfma_f32_16x16x32_bf16 v[12:15], v[146:149], v[232:235], v[12:15]
	v_mfma_f32_16x16x32_bf16 v[8:11], v[178:181], v[232:235], v[8:11]
	v_mfma_f32_16x16x32_bf16 v[60:63], v[172:175], v[212:215], v[60:63]
	v_mfma_f32_16x16x32_bf16 v[56:59], v[182:185], v[212:215], v[56:59]
	v_mfma_f32_16x16x32_bf16 v[44:47], v[172:175], v[220:223], v[44:47]
	v_mfma_f32_16x16x32_bf16 v[40:43], v[182:185], v[220:223], v[40:43]
	v_mfma_f32_16x16x32_bf16 v[28:31], v[172:175], v[228:231], v[28:31]
	v_mfma_f32_16x16x32_bf16 v[24:27], v[182:185], v[228:231], v[24:27]
	v_mfma_f32_16x16x32_bf16 v[12:15], v[172:175], v[236:239], v[12:15]
	v_mfma_f32_16x16x32_bf16 v[8:11], v[182:185], v[236:239], v[8:11]
	s_setprio 0
	s_setprio 1
	v_mfma_f32_16x16x32_bf16 v[52:55], v[186:189], v[208:211], v[52:55]
	v_mfma_f32_16x16x32_bf16 v[48:51], v[200:203], v[208:211], v[48:51]
	v_mfma_f32_16x16x32_bf16 v[36:39], v[186:189], v[216:219], v[36:39]
	v_mfma_f32_16x16x32_bf16 v[32:35], v[200:203], v[216:219], v[32:35]
	v_mfma_f32_16x16x32_bf16 v[20:23], v[186:189], v[224:227], v[20:23]
	v_mfma_f32_16x16x32_bf16 v[16:19], v[200:203], v[224:227], v[16:19]
	v_mfma_f32_16x16x32_bf16 v[4:7], v[186:189], v[232:235], v[4:7]
	v_mfma_f32_16x16x32_bf16 v[0:3], v[200:203], v[232:235], v[0:3]
	v_mfma_f32_16x16x32_bf16 v[52:55], v[190:193], v[212:215], v[52:55]
	v_mfma_f32_16x16x32_bf16 v[48:51], v[204:207], v[212:215], v[48:51]
	v_mfma_f32_16x16x32_bf16 v[36:39], v[190:193], v[220:223], v[36:39]
	v_mfma_f32_16x16x32_bf16 v[32:35], v[204:207], v[220:223], v[32:35]
	v_mfma_f32_16x16x32_bf16 v[20:23], v[190:193], v[228:231], v[20:23]
	v_mfma_f32_16x16x32_bf16 v[16:19], v[204:207], v[228:231], v[16:19]
	v_mfma_f32_16x16x32_bf16 v[4:7], v[190:193], v[236:239], v[4:7]
	v_mfma_f32_16x16x32_bf16 v[0:3], v[204:207], v[236:239], v[0:3]
	s_setprio 0
	s_barrier
	s_add_i32 s23, 0, 0x18000
	v_add_u32_e32 v176, s23, v161
	s_add_i32 s26, 0, 0x1c000
	ds_read_b128 v[146:149], v176
	ds_read_b128 v[172:175], v176 offset:1024
	ds_read_b128 v[178:181], v176 offset:2048
	ds_read_b128 v[182:185], v176 offset:3072
	v_add_u32_e32 v176, s26, v161
	ds_read_b128 v[186:189], v176
	ds_read_b128 v[190:193], v176 offset:1024
	ds_read_b128 v[200:203], v176 offset:2048
	ds_read_b128 v[204:207], v176 offset:3072
	s_add_u32 s24, s84, 0x300000
	s_addc_u32 s25, s85, 0
	s_mov_b32 m0, s16
	v_lshl_add_u64 v[242:243], s[24:25], 0, v[128:129]
	ds_read_b128 v[208:211], v170 offset:32768
	ds_read_b128 v[212:215], v170 offset:33792
	ds_read_b128 v[216:219], v170 offset:34816
	ds_read_b128 v[220:223], v170 offset:35840
	ds_read_b128 v[224:227], v170 offset:36864
	ds_read_b128 v[228:231], v170 offset:37888
	ds_read_b128 v[232:235], v170 offset:38912
	ds_read_b128 v[236:239], v170 offset:39936
	global_load_lds_dwordx4 v[242:243], off
	v_lshl_add_u64 v[242:243], s[24:25], 0, v[132:133]
	s_mov_b32 m0, s17
	s_nop 0
	global_load_lds_dwordx4 v[242:243], off
	s_waitcnt vmcnt(8)
	s_waitcnt lgkmcnt(0)
	s_barrier
	s_setprio 1
	s_waitcnt lgkmcnt(0)
	v_mfma_f32_16x16x32_bf16 v[124:127], v[146:149], v[208:211], v[124:127]
	v_mfma_f32_16x16x32_bf16 v[120:123], v[178:181], v[208:211], v[120:123]
	v_mfma_f32_16x16x32_bf16 v[108:111], v[146:149], v[216:219], v[108:111]
	v_mfma_f32_16x16x32_bf16 v[104:107], v[178:181], v[216:219], v[104:107]
	v_mfma_f32_16x16x32_bf16 v[92:95], v[146:149], v[224:227], v[92:95]
	v_mfma_f32_16x16x32_bf16 v[88:91], v[178:181], v[224:227], v[88:91]
	v_mfma_f32_16x16x32_bf16 v[76:79], v[146:149], v[232:235], v[76:79]
	v_mfma_f32_16x16x32_bf16 v[72:75], v[178:181], v[232:235], v[72:75]
	v_mfma_f32_16x16x32_bf16 v[124:127], v[172:175], v[212:215], v[124:127]
	v_mfma_f32_16x16x32_bf16 v[120:123], v[182:185], v[212:215], v[120:123]
	v_mfma_f32_16x16x32_bf16 v[108:111], v[172:175], v[220:223], v[108:111]
	v_mfma_f32_16x16x32_bf16 v[104:107], v[182:185], v[220:223], v[104:107]
	v_mfma_f32_16x16x32_bf16 v[92:95], v[172:175], v[228:231], v[92:95]
	v_mfma_f32_16x16x32_bf16 v[88:91], v[182:185], v[228:231], v[88:91]
	v_mfma_f32_16x16x32_bf16 v[76:79], v[172:175], v[236:239], v[76:79]
	v_mfma_f32_16x16x32_bf16 v[72:75], v[182:185], v[236:239], v[72:75]
	s_setprio 0
	s_setprio 1
	v_mfma_f32_16x16x32_bf16 v[116:119], v[186:189], v[208:211], v[116:119]
	v_mfma_f32_16x16x32_bf16 v[112:115], v[200:203], v[208:211], v[112:115]
	v_mfma_f32_16x16x32_bf16 v[100:103], v[186:189], v[216:219], v[100:103]
	v_mfma_f32_16x16x32_bf16 v[96:99], v[200:203], v[216:219], v[96:99]
	v_mfma_f32_16x16x32_bf16 v[84:87], v[186:189], v[224:227], v[84:87]
	v_mfma_f32_16x16x32_bf16 v[80:83], v[200:203], v[224:227], v[80:83]
	v_mfma_f32_16x16x32_bf16 v[68:71], v[186:189], v[232:235], v[68:71]
	v_mfma_f32_16x16x32_bf16 v[64:67], v[200:203], v[232:235], v[64:67]
	v_mfma_f32_16x16x32_bf16 v[116:119], v[190:193], v[212:215], v[116:119]
	v_mfma_f32_16x16x32_bf16 v[112:115], v[204:207], v[212:215], v[112:115]
	v_mfma_f32_16x16x32_bf16 v[100:103], v[190:193], v[220:223], v[100:103]
	v_mfma_f32_16x16x32_bf16 v[96:99], v[204:207], v[220:223], v[96:99]
	v_mfma_f32_16x16x32_bf16 v[84:87], v[190:193], v[228:231], v[84:87]
	v_mfma_f32_16x16x32_bf16 v[80:83], v[204:207], v[228:231], v[80:83]
	v_mfma_f32_16x16x32_bf16 v[68:71], v[190:193], v[236:239], v[68:71]
	v_mfma_f32_16x16x32_bf16 v[64:67], v[204:207], v[236:239], v[64:67]
	s_setprio 0
	s_barrier
; #define PG8_STAGE(bufoff, gbase, voff) do { _Pragma("unroll") for (int _i = 0; _i < 2; ++_i) \
;         __builtin_amdgcn_global_load_lds((const unsigned*)((const char*)(gbase) + (voff)[_i]), (LAS unsigned*)(lds + (bufoff) + ldsw + _i * 8192), 16, 0, 0); } while (0)
; #define PG8_LDA(dst, b, h) do { _Pragma("unroll") for (int m = 0; m < 4; ++m) _Pragma("unroll") for (int k = 0; k < 2; ++k) dst[m][k] = *(const LAS bf16x8*)(lds + PG8_SA(b, h) + aoff + m * 2048 + k * 1024); } while (0)
; #define PG8_MMA(ai, bj, At, Bt) do { __builtin_amdgcn_s_setprio(1); _Pragma("unroll") for (int m = 0; m < 4; ++m) _Pragma("unroll") for (int n = 0; n < 2; ++n) _Pragma("unroll") for (int k = 0; k < 2; ++k) \
;         acc[ai][bj][m][n] = __builtin_amdgcn_mfma_f32_16x16x32_bf16(Bt[n][k], At[m][k], acc[ai][bj][m][n], 0, 0, 0); __builtin_amdgcn_s_setprio(0); } while (0)
; #define PG8_WAIT_V(n) asm volatile("s_waitcnt vmcnt(" #n ")" ::: "memory")
; #define PG8_WAIT_L(n) asm volatile("s_waitcnt lgkmcnt(" #n ")" ::: "memory")
; #define PG8_BAR __builtin_amdgcn_s_barrier()
; #define PG8_SCHED __builtin_amdgcn_sched_barrier(0)
; template <class Epi, int K, int lda, class Sched = StaticOrder, bool ALIGN_EPI = true>
; __device__ __forceinline__ void gemm_phase(LAS unsigned char* lds, const Gemm g, const Sched& S, const Epi& E) {
;     ...
;             PG8_LDA(At, 1, 1); PG8_STAGE(PG8_SB(1, 0), b3, voffB); PG8_STAGE(PG8_SB(1, 1), b3 + hstepB, voffB); PG8_STAGE(PG8_SA(1, 0), a3, voffA);
;             PG8_WAIT_V(8); PG8_WAIT_L(0); PG8_BAR; PG8_MMA(1, 0, At, B0); PG8_MMA(1, 1, At, B1); PG8_BAR; PG8_SCHED;
;         }
;         if constexpr (ALIGN_EPI) { if (wr == 0) PG8_BAR; }
	s_add_i32 s23, s23, s87
	v_lshl_add_u64 v[150:151], v[150:151], 0, s[66:67]
	s_mov_b32 m0, s23
	ds_read_b128 v[208:211], v170 offset:49152
	ds_read_b128 v[212:215], v170 offset:50176
	ds_read_b128 v[216:219], v170 offset:51200
	ds_read_b128 v[220:223], v170 offset:52224
	ds_read_b128 v[224:227], v170 offset:53248
	ds_read_b128 v[228:231], v170 offset:54272
	ds_read_b128 v[232:235], v170 offset:55296
	ds_read_b128 v[236:239], v170 offset:56320
	global_load_lds_dwordx4 v[150:151], off
	s_add_i32 m0, s23, 0x2000
	s_add_u32 s24, s82, 0x100080
	v_lshl_add_u64 v[150:151], v[194:195], 0, s[66:67]
	s_addc_u32 s25, s83, 0
	s_add_i32 s23, s26, s87
	global_load_lds_dwordx4 v[150:151], off
	v_lshl_add_u64 v[150:151], s[24:25], 0, v[130:131]
	s_mov_b32 m0, s23
	s_nop 0
	global_load_lds_dwordx4 v[150:151], off
	v_lshl_add_u64 v[150:151], s[24:25], 0, v[134:135]
	s_add_i32 m0, s23, 0x2000
	s_nop 0
	global_load_lds_dwordx4 v[150:151], off
	v_lshl_add_u64 v[150:151], v[196:197], 0, s[66:67]
	s_mov_b32 m0, s18
	s_nop 0
	global_load_lds_dwordx4 v[150:151], off
	v_lshl_add_u64 v[150:151], v[240:241], 0, s[66:67]
	s_mov_b32 m0, s19
	s_nop 0
	global_load_lds_dwordx4 v[150:151], off
	s_waitcnt vmcnt(8)
	s_waitcnt lgkmcnt(0)
	s_barrier
	s_setprio 1
	s_waitcnt lgkmcnt(0)
	v_mfma_f32_16x16x32_bf16 v[60:63], v[146:149], v[208:211], v[60:63]
	v_mfma_f32_16x16x32_bf16 v[56:59], v[178:181], v[208:211], v[56:59]
	v_mfma_f32_16x16x32_bf16 v[44:47], v[146:149], v[216:219], v[44:47]
	v_mfma_f32_16x16x32_bf16 v[40:43], v[178:181], v[216:219], v[40:43]
	v_mfma_f32_16x16x32_bf16 v[28:31], v[146:149], v[224:227], v[28:31]
	v_mfma_f32_16x16x32_bf16 v[24:27], v[178:181], v[224:227], v[24:27]
	v_mfma_f32_16x16x32_bf16 v[12:15], v[146:149], v[232:235], v[12:15]
	v_mfma_f32_16x16x32_bf16 v[8:11], v[178:181], v[232:235], v[8:11]
	v_mfma_f32_16x16x32_bf16 v[60:63], v[172:175], v[212:215], v[60:63]
	v_mfma_f32_16x16x32_bf16 v[56:59], v[182:185], v[212:215], v[56:59]
	v_mfma_f32_16x16x32_bf16 v[44:47], v[172:175], v[220:223], v[44:47]
	v_mfma_f32_16x16x32_bf16 v[40:43], v[182:185], v[220:223], v[40:43]
	v_mfma_f32_16x16x32_bf16 v[28:31], v[172:175], v[228:231], v[28:31]
	v_mfma_f32_16x16x32_bf16 v[24:27], v[182:185], v[228:231], v[24:27]
	v_mfma_f32_16x16x32_bf16 v[12:15], v[172:175], v[236:239], v[12:15]
	v_mfma_f32_16x16x32_bf16 v[8:11], v[182:185], v[236:239], v[8:11]
	s_setprio 0
	s_setprio 1
	v_mfma_f32_16x16x32_bf16 v[52:55], v[186:189], v[208:211], v[52:55]
	v_mfma_f32_16x16x32_bf16 v[48:51], v[200:203], v[208:211], v[48:51]
	v_mfma_f32_16x16x32_bf16 v[36:39], v[186:189], v[216:219], v[36:39]
	v_mfma_f32_16x16x32_bf16 v[32:35], v[200:203], v[216:219], v[32:35]
	v_mfma_f32_16x16x32_bf16 v[20:23], v[186:189], v[224:227], v[20:23]
	v_mfma_f32_16x16x32_bf16 v[16:19], v[200:203], v[224:227], v[16:19]
	v_mfma_f32_16x16x32_bf16 v[4:7], v[186:189], v[232:235], v[4:7]
	v_mfma_f32_16x16x32_bf16 v[0:3], v[200:203], v[232:235], v[0:3]
	v_mfma_f32_16x16x32_bf16 v[52:55], v[190:193], v[212:215], v[52:55]
	v_mfma_f32_16x16x32_bf16 v[48:51], v[204:207], v[212:215], v[48:51]
	v_mfma_f32_16x16x32_bf16 v[36:39], v[190:193], v[220:223], v[36:39]
	v_mfma_f32_16x16x32_bf16 v[32:35], v[204:207], v[220:223], v[32:35]
	v_mfma_f32_16x16x32_bf16 v[20:23], v[190:193], v[228:231], v[20:23]
	v_mfma_f32_16x16x32_bf16 v[16:19], v[204:207], v[228:231], v[16:19]
	v_mfma_f32_16x16x32_bf16 v[4:7], v[190:193], v[236:239], v[4:7]
	v_mfma_f32_16x16x32_bf16 v[0:3], v[204:207], v[236:239], v[0:3]
	s_setprio 0
	s_add_i32 s22, s22, 2
	s_add_u32 s78, s78, 0x100
	s_addc_u32 s79, s79, 0
	s_cmp_gt_u32 s22, 61
	s_mov_b64 s[40:41], s[80:81]
	s_barrier
	s_cbranch_scc0 .LBB0_366
	s_and_b64 vcc, exec, s[74:75]
	s_cbranch_vccz .LBB0_369
	s_barrier

; #define PG8_STAGE(bufoff, gbase, voff) do { _Pragma("unroll") for (int _i = 0; _i < 2; ++_i) \
;         __builtin_amdgcn_global_load_lds((const unsigned*)((const char*)(gbase) + (voff)[_i]), (LAS unsigned*)(lds + (bufoff) + ldsw + _i * 8192), 16, 0, 0); } while (0)
; #define PG8_LDA(dst, b, h) do { _Pragma("unroll") for (int m = 0; m < 4; ++m) _Pragma("unroll") for (int k = 0; k < 2; ++k) dst[m][k] = *(const LAS bf16x8*)(lds + PG8_SA(b, h) + aoff + m * 2048 + k * 1024); } while (0)
; #define PG8_LDB(dst, b, h) do { _Pragma("unroll") for (int n = 0; n < 2; ++n) _Pragma("unroll") for (int k = 0; k < 2; ++k) dst[n][k] = *(const LAS bf16x8*)(lds + PG8_SB(b, h) + boff + n * 2048 + k * 1024); } while (0)
; #define PG8_MMA(ai, bj, At, Bt) do { __builtin_amdgcn_s_setprio(1); _Pragma("unroll") for (int m = 0; m < 4; ++m) _Pragma("unroll") for (int n = 0; n < 2; ++n) _Pragma("unroll") for (int k = 0; k < 2; ++k) \
;         acc[ai][bj][m][n] = __builtin_amdgcn_mfma_f32_16x16x32_bf16(Bt[n][k], At[m][k], acc[ai][bj][m][n], 0, 0, 0); __builtin_amdgcn_s_setprio(0); } while (0)
; #define PG8_WAIT_V(n) asm volatile("s_waitcnt vmcnt(" #n ")" ::: "memory")
; #define PG8_WAIT_L(n) asm volatile("s_waitcnt lgkmcnt(" #n ")" ::: "memory")
; #define PG8_BAR __builtin_amdgcn_s_barrier()
; #define PG8_SCHED __builtin_amdgcn_sched_barrier(0)
; template <class Epi, int K, int lda, class Sched = StaticOrder, bool ALIGN_EPI = true>
; __device__ __forceinline__ void gemm_phase(LAS unsigned char* lds, const Gemm g, const Sched& S, const Epi& E) {
;     ...
;             const bool last = (t == nt - 2);
;             const char* a1 = cA + (size_t)(t + 1) * kstep;
;             const char* a2 = last ? nA : cA + (size_t)(t + 2) * kstep; const char* b2 = last ? nB : cB + (size_t)(t + 2) * kstep;
;             const char* a3 = a2 + kstep; const char* b3 = b2 + kstep;
;             PG8_LDB(B0, 0, 0); PG8_LDB(B1, 0, 1); PG8_SCHED; PG8_LDA(At, 0, 0); PG8_STAGE(PG8_SA(1, 1), a1 + hstepA, voffA);
;             PG8_WAIT_V(8); PG8_WAIT_L(0); PG8_BAR; PG8_MMA(0, 0, At, B0); PG8_MMA(0, 1, At, B1); PG8_BAR; PG8_SCHED;
;             PG8_LDA(At, 0, 1); PG8_STAGE(PG8_SB(0, 0), b2, voffB); PG8_STAGE(PG8_SB(0, 1), b2 + hstepB, voffB); PG8_STAGE(PG8_SA(0, 0), a2, voffA);
;             PG8_WAIT_V(8); PG8_WAIT_L(0); PG8_BAR; PG8_MMA(1, 0, At, B0); PG8_MMA(1, 1, At, B1); PG8_BAR; PG8_SCHED;
.LBB0_474:
	s_add_i32 s24, 0, 0x10000
	s_add_i32 s25, 0, 0x14000
	v_add_u32_e32 v160, s24, v170
	ds_read_b128 v[156:159], v160
	ds_read_b128 v[182:185], v160 offset:1024
	ds_read_b128 v[186:189], v160 offset:2048
	ds_read_b128 v[190:193], v160 offset:3072
	v_add_u32_e32 v160, s25, v170
	ds_read_b128 v[200:203], v160
	ds_read_b128 v[204:207], v160 offset:1024
	ds_read_b128 v[208:211], v160 offset:2048
	ds_read_b128 v[212:215], v160 offset:3072
	s_add_u32 s22, s38, 0xfff80080
	s_addc_u32 s23, s39, -1
	s_cmp_eq_u32 s21, 28
	s_cselect_b32 s79, s19, s23
	s_cselect_b32 s78, s20, s22
	s_cselect_b32 s77, s41, s75
	s_cselect_b32 s76, s40, s74
	v_lshl_add_u64 v[160:161], s[38:39], 0, v[152:153]
	s_add_i32 m0, s14, 0xc000
	ds_read_b128 v[216:219], v179
	ds_read_b128 v[220:223], v179 offset:1024
	ds_read_b128 v[224:227], v179 offset:2048
	ds_read_b128 v[228:231], v179 offset:3072
	ds_read_b128 v[232:235], v179 offset:4096
	ds_read_b128 v[236:239], v179 offset:5120
	ds_read_b128 v[240:243], v179 offset:6144
	ds_read_b128 v[244:247], v179 offset:7168
	global_load_lds_dwordx4 v[160:161], off
	v_lshl_add_u64 v[160:161], s[38:39], 0, v[154:155]
	s_add_i32 m0, s14, 0xe000
	s_nop 0
	global_load_lds_dwordx4 v[160:161], off
	s_waitcnt vmcnt(8)
	s_waitcnt lgkmcnt(0)
	s_barrier
	s_setprio 1
	s_waitcnt lgkmcnt(0)
	v_mfma_f32_16x16x32_bf16 v[124:127], v[156:159], v[216:219], v[124:127]
	v_mfma_f32_16x16x32_bf16 v[120:123], v[186:189], v[216:219], v[120:123]
	v_mfma_f32_16x16x32_bf16 v[108:111], v[156:159], v[224:227], v[108:111]
	v_mfma_f32_16x16x32_bf16 v[104:107], v[186:189], v[224:227], v[104:107]
	v_mfma_f32_16x16x32_bf16 v[92:95], v[156:159], v[232:235], v[92:95]
	v_mfma_f32_16x16x32_bf16 v[88:91], v[186:189], v[232:235], v[88:91]
	v_mfma_f32_16x16x32_bf16 v[76:79], v[156:159], v[240:243], v[76:79]
	v_mfma_f32_16x16x32_bf16 v[72:75], v[186:189], v[240:243], v[72:75]
	v_mfma_f32_16x16x32_bf16 v[124:127], v[182:185], v[220:223], v[124:127]
	v_mfma_f32_16x16x32_bf16 v[120:123], v[190:193], v[220:223], v[120:123]
	v_mfma_f32_16x16x32_bf16 v[108:111], v[182:185], v[228:231], v[108:111]
	v_mfma_f32_16x16x32_bf16 v[104:107], v[190:193], v[228:231], v[104:107]
	v_mfma_f32_16x16x32_bf16 v[92:95], v[182:185], v[236:239], v[92:95]
	v_mfma_f32_16x16x32_bf16 v[88:91], v[190:193], v[236:239], v[88:91]
	v_mfma_f32_16x16x32_bf16 v[76:79], v[182:185], v[244:247], v[76:79]
	v_mfma_f32_16x16x32_bf16 v[72:75], v[190:193], v[244:247], v[72:75]
	s_setprio 0
	s_setprio 1
	v_mfma_f32_16x16x32_bf16 v[116:119], v[200:203], v[216:219], v[116:119]
	v_mfma_f32_16x16x32_bf16 v[112:115], v[208:211], v[216:219], v[112:115]
	v_mfma_f32_16x16x32_bf16 v[100:103], v[200:203], v[224:227], v[100:103]
	v_mfma_f32_16x16x32_bf16 v[96:99], v[208:211], v[224:227], v[96:99]
	v_mfma_f32_16x16x32_bf16 v[84:87], v[200:203], v[232:235], v[84:87]
	v_mfma_f32_16x16x32_bf16 v[80:83], v[208:211], v[232:235], v[80:83]
	v_mfma_f32_16x16x32_bf16 v[68:71], v[200:203], v[240:243], v[68:71]
	v_mfma_f32_16x16x32_bf16 v[64:67], v[208:211], v[240:243], v[64:67]
	v_mfma_f32_16x16x32_bf16 v[116:119], v[204:207], v[220:223], v[116:119]
	v_mfma_f32_16x16x32_bf16 v[112:115], v[212:215], v[220:223], v[112:115]
	v_mfma_f32_16x16x32_bf16 v[100:103], v[204:207], v[228:231], v[100:103]
	v_mfma_f32_16x16x32_bf16 v[96:99], v[212:215], v[228:231], v[96:99]
	v_mfma_f32_16x16x32_bf16 v[84:87], v[204:207], v[236:239], v[84:87]
	v_mfma_f32_16x16x32_bf16 v[80:83], v[212:215], v[236:239], v[80:83]
	v_mfma_f32_16x16x32_bf16 v[68:71], v[204:207], v[244:247], v[68:71]
	v_mfma_f32_16x16x32_bf16 v[64:67], v[212:215], v[244:247], v[64:67]
	s_setprio 0
	s_barrier
	s_add_i32 s22, s24, s80
	v_lshl_add_u64 v[160:161], s[76:77], 0, v[176:177]
	s_mov_b32 m0, s22
	ds_read_b128 v[216:219], v179 offset:16384
	ds_read_b128 v[220:223], v179 offset:17408
	ds_read_b128 v[224:227], v179 offset:18432
	ds_read_b128 v[228:231], v179 offset:19456
	ds_read_b128 v[232:235], v179 offset:20480
	ds_read_b128 v[236:239], v179 offset:21504
	ds_read_b128 v[240:243], v179 offset:22528
	ds_read_b128 v[244:247], v179 offset:23552
	global_load_lds_dwordx4 v[160:161], off
	s_add_i32 m0, s22, 0x2000
	s_add_u32 s22, s76, 0x80000
	v_lshl_add_u64 v[248:249], s[76:77], 0, v[128:129]
	s_addc_u32 s23, s77, 0
	s_add_i32 s24, s25, s80
	global_load_lds_dwordx4 v[248:249], off
	v_lshl_add_u64 v[250:251], s[22:23], 0, v[176:177]
	s_mov_b32 m0, s24
	v_lshl_add_u64 v[196:197], s[78:79], 0, v[128:129]
	global_load_lds_dwordx4 v[250:251], off
	v_lshl_add_u64 v[250:251], s[22:23], 0, v[128:129]
	s_add_i32 m0, s24, 0x2000
	s_nop 0
	global_load_lds_dwordx4 v[250:251], off
	v_lshl_add_u64 v[250:251], s[78:79], 0, v[176:177]
	s_mov_b32 m0, s14
	s_nop 0
	global_load_lds_dwordx4 v[250:251], off
	s_mov_b32 m0, s15
	s_nop 0
	global_load_lds_dwordx4 v[196:197], off
	s_waitcnt vmcnt(8)
	s_waitcnt lgkmcnt(0)
	s_barrier
; #define PG8_STAGE(bufoff, gbase, voff) do { _Pragma("unroll") for (int _i = 0; _i < 2; ++_i) \
;         __builtin_amdgcn_global_load_lds((const unsigned*)((const char*)(gbase) + (voff)[_i]), (LAS unsigned*)(lds + (bufoff) + ldsw + _i * 8192), 16, 0, 0); } while (0)
; #define PG8_LDA(dst, b, h) do { _Pragma("unroll") for (int m = 0; m < 4; ++m) _Pragma("unroll") for (int k = 0; k < 2; ++k) dst[m][k] = *(const LAS bf16x8*)(lds + PG8_SA(b, h) + aoff + m * 2048 + k * 1024); } while (0)
; #define PG8_LDB(dst, b, h) do { _Pragma("unroll") for (int n = 0; n < 2; ++n) _Pragma("unroll") for (int k = 0; k < 2; ++k) dst[n][k] = *(const LAS bf16x8*)(lds + PG8_SB(b, h) + boff + n * 2048 + k * 1024); } while (0)
; #define PG8_MMA(ai, bj, At, Bt) do { __builtin_amdgcn_s_setprio(1); _Pragma("unroll") for (int m = 0; m < 4; ++m) _Pragma("unroll") for (int n = 0; n < 2; ++n) _Pragma("unroll") for (int k = 0; k < 2; ++k) \
;         acc[ai][bj][m][n] = __builtin_amdgcn_mfma_f32_16x16x32_bf16(Bt[n][k], At[m][k], acc[ai][bj][m][n], 0, 0, 0); __builtin_amdgcn_s_setprio(0); } while (0)
; #define PG8_WAIT_V(n) asm volatile("s_waitcnt vmcnt(" #n ")" ::: "memory")
; #define PG8_WAIT_L(n) asm volatile("s_waitcnt lgkmcnt(" #n ")" ::: "memory")
; #define PG8_BAR __builtin_amdgcn_s_barrier()
; #define PG8_SCHED __builtin_amdgcn_sched_barrier(0)
; template <class Epi, int K, int lda, class Sched = StaticOrder, bool ALIGN_EPI = true>
; __device__ __forceinline__ void gemm_phase(LAS unsigned char* lds, const Gemm g, const Sched& S, const Epi& E) {
;     ...
;             PG8_WAIT_V(8); PG8_WAIT_L(0); PG8_BAR; PG8_MMA(1, 0, At, B0); PG8_MMA(1, 1, At, B1); PG8_BAR; PG8_SCHED;
;             PG8_LDB(B0, 1, 0); PG8_LDB(B1, 1, 1); PG8_SCHED; PG8_LDA(At, 1, 0); PG8_STAGE(PG8_SA(0, 1), a2 + hstepA, voffA);
;             PG8_WAIT_V(8); PG8_WAIT_L(0); PG8_BAR; PG8_MMA(0, 0, At, B0); PG8_MMA(0, 1, At, B1); PG8_BAR; PG8_SCHED;
	s_setprio 1
	s_waitcnt lgkmcnt(0)
	v_mfma_f32_16x16x32_bf16 v[60:63], v[156:159], v[216:219], v[60:63]
	v_mfma_f32_16x16x32_bf16 v[56:59], v[186:189], v[216:219], v[56:59]
	v_mfma_f32_16x16x32_bf16 v[44:47], v[156:159], v[224:227], v[44:47]
	v_mfma_f32_16x16x32_bf16 v[40:43], v[186:189], v[224:227], v[40:43]
	v_mfma_f32_16x16x32_bf16 v[28:31], v[156:159], v[232:235], v[28:31]
	v_mfma_f32_16x16x32_bf16 v[24:27], v[186:189], v[232:235], v[24:27]
	v_mfma_f32_16x16x32_bf16 v[12:15], v[156:159], v[240:243], v[12:15]
	v_mfma_f32_16x16x32_bf16 v[8:11], v[186:189], v[240:243], v[8:11]
	v_mfma_f32_16x16x32_bf16 v[60:63], v[182:185], v[220:223], v[60:63]
	v_mfma_f32_16x16x32_bf16 v[56:59], v[190:193], v[220:223], v[56:59]
	v_mfma_f32_16x16x32_bf16 v[44:47], v[182:185], v[228:231], v[44:47]
	v_mfma_f32_16x16x32_bf16 v[40:43], v[190:193], v[228:231], v[40:43]
	v_mfma_f32_16x16x32_bf16 v[28:31], v[182:185], v[236:239], v[28:31]
	v_mfma_f32_16x16x32_bf16 v[24:27], v[190:193], v[236:239], v[24:27]
	v_mfma_f32_16x16x32_bf16 v[12:15], v[182:185], v[244:247], v[12:15]
	v_mfma_f32_16x16x32_bf16 v[8:11], v[190:193], v[244:247], v[8:11]
	s_setprio 0
	s_setprio 1
	v_mfma_f32_16x16x32_bf16 v[52:55], v[200:203], v[216:219], v[52:55]
	v_mfma_f32_16x16x32_bf16 v[48:51], v[208:211], v[216:219], v[48:51]
	v_mfma_f32_16x16x32_bf16 v[36:39], v[200:203], v[224:227], v[36:39]
	v_mfma_f32_16x16x32_bf16 v[32:35], v[208:211], v[224:227], v[32:35]
	v_mfma_f32_16x16x32_bf16 v[20:23], v[200:203], v[232:235], v[20:23]
	v_mfma_f32_16x16x32_bf16 v[16:19], v[208:211], v[232:235], v[16:19]
	v_mfma_f32_16x16x32_bf16 v[4:7], v[200:203], v[240:243], v[4:7]
	v_mfma_f32_16x16x32_bf16 v[0:3], v[208:211], v[240:243], v[0:3]
	v_mfma_f32_16x16x32_bf16 v[52:55], v[204:207], v[220:223], v[52:55]
	v_mfma_f32_16x16x32_bf16 v[48:51], v[212:215], v[220:223], v[48:51]
	v_mfma_f32_16x16x32_bf16 v[36:39], v[204:207], v[228:231], v[36:39]
	v_mfma_f32_16x16x32_bf16 v[32:35], v[212:215], v[228:231], v[32:35]
	v_mfma_f32_16x16x32_bf16 v[20:23], v[204:207], v[236:239], v[20:23]
	v_mfma_f32_16x16x32_bf16 v[16:19], v[212:215], v[236:239], v[16:19]
	v_mfma_f32_16x16x32_bf16 v[4:7], v[204:207], v[244:247], v[4:7]
	v_mfma_f32_16x16x32_bf16 v[0:3], v[212:215], v[244:247], v[0:3]
	s_setprio 0
	s_barrier
	s_add_i32 s24, 0, 0x18000
	v_add_u32_e32 v181, s24, v170
	s_add_i32 s25, 0, 0x1c000
	ds_read_b128 v[156:159], v181
	ds_read_b128 v[182:185], v181 offset:1024
	ds_read_b128 v[186:189], v181 offset:2048
	ds_read_b128 v[190:193], v181 offset:3072
	v_add_u32_e32 v181, s25, v170
	ds_read_b128 v[200:203], v181
	ds_read_b128 v[204:207], v181 offset:1024
	ds_read_b128 v[208:211], v181 offset:2048
	ds_read_b128 v[212:215], v181 offset:3072
	s_add_u32 s22, s78, 0x80000
	s_addc_u32 s23, s79, 0
	s_mov_b32 m0, s16
	v_lshl_add_u64 v[194:195], s[22:23], 0, v[176:177]
	ds_read_b128 v[216:219], v179 offset:32768
	ds_read_b128 v[220:223], v179 offset:33792
	ds_read_b128 v[224:227], v179 offset:34816
	ds_read_b128 v[228:231], v179 offset:35840
	ds_read_b128 v[232:235], v179 offset:36864
	ds_read_b128 v[236:239], v179 offset:37888
	ds_read_b128 v[240:243], v179 offset:38912
	ds_read_b128 v[244:247], v179 offset:39936
	global_load_lds_dwordx4 v[194:195], off
	v_lshl_add_u64 v[194:195], s[22:23], 0, v[128:129]
	s_mov_b32 m0, s17
	s_nop 0
	global_load_lds_dwordx4 v[194:195], off
	s_waitcnt vmcnt(8)
	s_waitcnt lgkmcnt(0)
	s_barrier
	s_setprio 1
	s_waitcnt lgkmcnt(0)
	v_mfma_f32_16x16x32_bf16 v[124:127], v[156:159], v[216:219], v[124:127]
	v_mfma_f32_16x16x32_bf16 v[120:123], v[186:189], v[216:219], v[120:123]
	v_mfma_f32_16x16x32_bf16 v[108:111], v[156:159], v[224:227], v[108:111]
	v_mfma_f32_16x16x32_bf16 v[104:107], v[186:189], v[224:227], v[104:107]
	v_mfma_f32_16x16x32_bf16 v[92:95], v[156:159], v[232:235], v[92:95]
	v_mfma_f32_16x16x32_bf16 v[88:91], v[186:189], v[232:235], v[88:91]
	v_mfma_f32_16x16x32_bf16 v[76:79], v[156:159], v[240:243], v[76:79]
	v_mfma_f32_16x16x32_bf16 v[72:75], v[186:189], v[240:243], v[72:75]
	v_mfma_f32_16x16x32_bf16 v[124:127], v[182:185], v[220:223], v[124:127]
	v_mfma_f32_16x16x32_bf16 v[120:123], v[190:193], v[220:223], v[120:123]
	v_mfma_f32_16x16x32_bf16 v[108:111], v[182:185], v[228:231], v[108:111]
	v_mfma_f32_16x16x32_bf16 v[104:107], v[190:193], v[228:231], v[104:107]
	v_mfma_f32_16x16x32_bf16 v[92:95], v[182:185], v[236:239], v[92:95]
	v_mfma_f32_16x16x32_bf16 v[88:91], v[190:193], v[236:239], v[88:91]
	v_mfma_f32_16x16x32_bf16 v[76:79], v[182:185], v[244:247], v[76:79]
	v_mfma_f32_16x16x32_bf16 v[72:75], v[190:193], v[244:247], v[72:75]
	s_setprio 0
	s_setprio 1
	v_mfma_f32_16x16x32_bf16 v[116:119], v[200:203], v[216:219], v[116:119]
	v_mfma_f32_16x16x32_bf16 v[112:115], v[208:211], v[216:219], v[112:115]
	v_mfma_f32_16x16x32_bf16 v[100:103], v[200:203], v[224:227], v[100:103]
	v_mfma_f32_16x16x32_bf16 v[96:99], v[208:211], v[224:227], v[96:99]
	v_mfma_f32_16x16x32_bf16 v[84:87], v[200:203], v[232:235], v[84:87]
	v_mfma_f32_16x16x32_bf16 v[80:83], v[208:211], v[232:235], v[80:83]
	v_mfma_f32_16x16x32_bf16 v[68:71], v[200:203], v[240:243], v[68:71]
	v_mfma_f32_16x16x32_bf16 v[64:67], v[208:211], v[240:243], v[64:67]
	v_mfma_f32_16x16x32_bf16 v[116:119], v[204:207], v[220:223], v[116:119]
	v_mfma_f32_16x16x32_bf16 v[112:115], v[212:215], v[220:223], v[112:115]
	v_mfma_f32_16x16x32_bf16 v[100:103], v[204:207], v[228:231], v[100:103]
	v_mfma_f32_16x16x32_bf16 v[96:99], v[212:215], v[228:231], v[96:99]
	v_mfma_f32_16x16x32_bf16 v[84:87], v[204:207], v[236:239], v[84:87]
	v_mfma_f32_16x16x32_bf16 v[80:83], v[212:215], v[236:239], v[80:83]
	v_mfma_f32_16x16x32_bf16 v[68:71], v[204:207], v[244:247], v[68:71]
	v_mfma_f32_16x16x32_bf16 v[64:67], v[212:215], v[244:247], v[64:67]
	s_setprio 0
	s_barrier
; #define PG8_STAGE(bufoff, gbase, voff) do { _Pragma("unroll") for (int _i = 0; _i < 2; ++_i) \
;         __builtin_amdgcn_global_load_lds((const unsigned*)((const char*)(gbase) + (voff)[_i]), (LAS unsigned*)(lds + (bufoff) + ldsw + _i * 8192), 16, 0, 0); } while (0)
; #define PG8_LDA(dst, b, h) do { _Pragma("unroll") for (int m = 0; m < 4; ++m) _Pragma("unroll") for (int k = 0; k < 2; ++k) dst[m][k] = *(const LAS bf16x8*)(lds + PG8_SA(b, h) + aoff + m * 2048 + k * 1024); } while (0)
; #define PG8_MMA(ai, bj, At, Bt) do { __builtin_amdgcn_s_setprio(1); _Pragma("unroll") for (int m = 0; m < 4; ++m) _Pragma("unroll") for (int n = 0; n < 2; ++n) _Pragma("unroll") for (int k = 0; k < 2; ++k) \
;         acc[ai][bj][m][n] = __builtin_amdgcn_mfma_f32_16x16x32_bf16(Bt[n][k], At[m][k], acc[ai][bj][m][n], 0, 0, 0); __builtin_amdgcn_s_setprio(0); } while (0)
; #define PG8_WAIT_V(n) asm volatile("s_waitcnt vmcnt(" #n ")" ::: "memory")
; #define PG8_WAIT_L(n) asm volatile("s_waitcnt lgkmcnt(" #n ")" ::: "memory")
; #define PG8_BAR __builtin_amdgcn_s_barrier()
; #define PG8_SCHED __builtin_amdgcn_sched_barrier(0)
; template <class Epi, int K, int lda, class Sched = StaticOrder, bool ALIGN_EPI = true>
; __device__ __forceinline__ void gemm_phase(LAS unsigned char* lds, const Gemm g, const Sched& S, const Epi& E) {
;     ...
;             PG8_LDA(At, 1, 1); PG8_STAGE(PG8_SB(1, 0), b3, voffB); PG8_STAGE(PG8_SB(1, 1), b3 + hstepB, voffB); PG8_STAGE(PG8_SA(1, 0), a3, voffA);
;             PG8_WAIT_V(8); PG8_WAIT_L(0); PG8_BAR; PG8_MMA(1, 0, At, B0); PG8_MMA(1, 1, At, B1); PG8_BAR; PG8_SCHED;
;         }
;         if constexpr (ALIGN_EPI) { if (wr == 0) PG8_BAR; }
	s_add_i32 s22, s24, s80
	v_lshl_add_u64 v[160:161], v[160:161], 0, s[66:67]
	s_mov_b32 m0, s22
	ds_read_b128 v[216:219], v179 offset:49152
	ds_read_b128 v[220:223], v179 offset:50176
	ds_read_b128 v[224:227], v179 offset:51200
	ds_read_b128 v[228:231], v179 offset:52224
	ds_read_b128 v[232:235], v179 offset:53248
	ds_read_b128 v[236:239], v179 offset:54272
	ds_read_b128 v[240:243], v179 offset:55296
	ds_read_b128 v[244:247], v179 offset:56320
	global_load_lds_dwordx4 v[160:161], off
	s_add_i32 m0, s22, 0x2000
	s_add_u32 s22, s76, 0x80080
	v_lshl_add_u64 v[160:161], v[248:249], 0, s[66:67]
	s_addc_u32 s23, s77, 0
	s_add_i32 s24, s25, s80
	global_load_lds_dwordx4 v[160:161], off
	v_lshl_add_u64 v[160:161], s[22:23], 0, v[176:177]
	s_mov_b32 m0, s24
	s_nop 0
	global_load_lds_dwordx4 v[160:161], off
	v_lshl_add_u64 v[160:161], s[22:23], 0, v[128:129]
	s_add_i32 m0, s24, 0x2000
	s_nop 0
	global_load_lds_dwordx4 v[160:161], off
	v_lshl_add_u64 v[160:161], v[250:251], 0, s[66:67]
	s_mov_b32 m0, s81
	s_nop 0
	global_load_lds_dwordx4 v[160:161], off
	v_lshl_add_u64 v[160:161], v[196:197], 0, s[66:67]
	s_mov_b32 m0, s82
	s_nop 0
	global_load_lds_dwordx4 v[160:161], off
	s_waitcnt vmcnt(8)
	s_waitcnt lgkmcnt(0)
	s_barrier
	s_setprio 1
	s_waitcnt lgkmcnt(0)
	v_mfma_f32_16x16x32_bf16 v[60:63], v[156:159], v[216:219], v[60:63]
	v_mfma_f32_16x16x32_bf16 v[56:59], v[186:189], v[216:219], v[56:59]
	v_mfma_f32_16x16x32_bf16 v[44:47], v[156:159], v[224:227], v[44:47]
	v_mfma_f32_16x16x32_bf16 v[40:43], v[186:189], v[224:227], v[40:43]
	v_mfma_f32_16x16x32_bf16 v[28:31], v[156:159], v[232:235], v[28:31]
	v_mfma_f32_16x16x32_bf16 v[24:27], v[186:189], v[232:235], v[24:27]
	v_mfma_f32_16x16x32_bf16 v[12:15], v[156:159], v[240:243], v[12:15]
	v_mfma_f32_16x16x32_bf16 v[8:11], v[186:189], v[240:243], v[8:11]
	v_mfma_f32_16x16x32_bf16 v[60:63], v[182:185], v[220:223], v[60:63]
	v_mfma_f32_16x16x32_bf16 v[56:59], v[190:193], v[220:223], v[56:59]
	v_mfma_f32_16x16x32_bf16 v[44:47], v[182:185], v[228:231], v[44:47]
	v_mfma_f32_16x16x32_bf16 v[40:43], v[190:193], v[228:231], v[40:43]
	v_mfma_f32_16x16x32_bf16 v[28:31], v[182:185], v[236:239], v[28:31]
	v_mfma_f32_16x16x32_bf16 v[24:27], v[190:193], v[236:239], v[24:27]
	v_mfma_f32_16x16x32_bf16 v[12:15], v[182:185], v[244:247], v[12:15]
	v_mfma_f32_16x16x32_bf16 v[8:11], v[190:193], v[244:247], v[8:11]
	s_setprio 0
	s_setprio 1
	v_mfma_f32_16x16x32_bf16 v[52:55], v[200:203], v[216:219], v[52:55]
	v_mfma_f32_16x16x32_bf16 v[48:51], v[208:211], v[216:219], v[48:51]
	v_mfma_f32_16x16x32_bf16 v[36:39], v[200:203], v[224:227], v[36:39]
	v_mfma_f32_16x16x32_bf16 v[32:35], v[208:211], v[224:227], v[32:35]
	v_mfma_f32_16x16x32_bf16 v[20:23], v[200:203], v[232:235], v[20:23]
	v_mfma_f32_16x16x32_bf16 v[16:19], v[208:211], v[232:235], v[16:19]
	v_mfma_f32_16x16x32_bf16 v[4:7], v[200:203], v[240:243], v[4:7]
	v_mfma_f32_16x16x32_bf16 v[0:3], v[208:211], v[240:243], v[0:3]
	v_mfma_f32_16x16x32_bf16 v[52:55], v[204:207], v[220:223], v[52:55]
	v_mfma_f32_16x16x32_bf16 v[48:51], v[212:215], v[220:223], v[48:51]
	v_mfma_f32_16x16x32_bf16 v[36:39], v[204:207], v[228:231], v[36:39]
	v_mfma_f32_16x16x32_bf16 v[32:35], v[212:215], v[228:231], v[32:35]
	v_mfma_f32_16x16x32_bf16 v[20:23], v[204:207], v[236:239], v[20:23]
	v_mfma_f32_16x16x32_bf16 v[16:19], v[212:215], v[236:239], v[16:19]
	v_mfma_f32_16x16x32_bf16 v[4:7], v[204:207], v[244:247], v[4:7]
	v_mfma_f32_16x16x32_bf16 v[0:3], v[212:215], v[244:247], v[0:3]
	s_setprio 0
	s_add_i32 s21, s21, 2
	s_add_u32 s38, s38, 0x100
	s_addc_u32 s39, s39, 0
	s_add_u32 s74, s74, 0x100
	s_addc_u32 s75, s75, 0
	s_cmp_gt_u32 s21, 29
	s_barrier
	s_cbranch_scc0 .LBB0_474
	s_and_b64 vcc, exec, s[52:53]
	s_cbranch_vccz .LBB0_477
	s_barrier
